# all 8 GEMM K-loops: SGPR-base LDS-DMA addressing + no-op setprio pair and redundant lgkmcnt(0) removed + remaining s_setprio bracket removed (MFMA path is barrier, 32 MFMA, barrier)
# speedup vs baseline: 1.0100x; 1.0032x over previous
.LBB0_432:
	ds_read_b128 v[150:153], v159
	ds_read_b128 v[154:157], v159 offset:1024
	ds_read_b128 v[162:165], v159 offset:2048
	ds_read_b128 v[166:169], v159 offset:3072
	ds_read_b128 v[170:173], v160
	ds_read_b128 v[174:177], v160 offset:1024
	ds_read_b128 v[178:181], v160 offset:2048
	ds_read_b128 v[182:185], v160 offset:3072
	s_add_u32 s42, s40, 0xfff00080
	s_addc_u32 s43, s41, -1
	s_cmp_eq_u32 s74, 60
	s_cselect_b32 s45, s35, s43
	s_cselect_b32 s44, s70, s42
	s_cselect_b32 s43, s31, s73
	s_cselect_b32 s42, s71, s72
	s_add_i32 m0, s55, 0xc000
	ds_read_b128 v[186:189], v161
	ds_read_b128 v[190:193], v161 offset:1024
	ds_read_b128 v[194:197], v161 offset:2048
	ds_read_b128 v[198:201], v161 offset:3072
	ds_read_b128 v[202:205], v161 offset:4096
	ds_read_b128 v[206:209], v161 offset:5120
	ds_read_b128 v[210:213], v161 offset:6144
	ds_read_b128 v[214:217], v161 offset:7168
	global_load_lds_dwordx4 v144, s[40:41]
	s_add_i32 m0, s55, 0xe000
	s_nop 0
	global_load_lds_dwordx4 v142, s[40:41]
	s_waitcnt vmcnt(8)
	s_waitcnt lgkmcnt(0)
	s_barrier
	v_mfma_f32_16x16x32_bf16 v[92:95], v[150:153], v[186:189], v[92:95]
	v_mfma_f32_16x16x32_bf16 v[88:91], v[162:165], v[186:189], v[88:91]
	v_mfma_f32_16x16x32_bf16 v[84:87], v[150:153], v[194:197], v[84:87]
	v_mfma_f32_16x16x32_bf16 v[80:83], v[162:165], v[194:197], v[80:83]
	v_mfma_f32_16x16x32_bf16 v[76:79], v[150:153], v[202:205], v[76:79]
	v_mfma_f32_16x16x32_bf16 v[68:71], v[162:165], v[202:205], v[68:71]
	v_mfma_f32_16x16x32_bf16 v[60:63], v[150:153], v[210:213], v[60:63]
	v_mfma_f32_16x16x32_bf16 v[56:59], v[162:165], v[210:213], v[56:59]
	v_mfma_f32_16x16x32_bf16 v[92:95], v[154:157], v[190:193], v[92:95]
	v_mfma_f32_16x16x32_bf16 v[88:91], v[166:169], v[190:193], v[88:91]
	v_mfma_f32_16x16x32_bf16 v[84:87], v[154:157], v[198:201], v[84:87]
	v_mfma_f32_16x16x32_bf16 v[80:83], v[166:169], v[198:201], v[80:83]
	v_mfma_f32_16x16x32_bf16 v[76:79], v[154:157], v[206:209], v[76:79]
	v_mfma_f32_16x16x32_bf16 v[68:71], v[166:169], v[206:209], v[68:71]
	v_mfma_f32_16x16x32_bf16 v[60:63], v[154:157], v[214:217], v[60:63]
	v_mfma_f32_16x16x32_bf16 v[56:59], v[166:169], v[214:217], v[56:59]
	v_mfma_f32_16x16x32_bf16 v[124:127], v[170:173], v[186:189], v[124:127]
	v_mfma_f32_16x16x32_bf16 v[120:123], v[178:181], v[186:189], v[120:123]
	v_mfma_f32_16x16x32_bf16 v[116:119], v[170:173], v[194:197], v[116:119]
	v_mfma_f32_16x16x32_bf16 v[112:115], v[178:181], v[194:197], v[112:115]
	v_mfma_f32_16x16x32_bf16 v[108:111], v[170:173], v[202:205], v[108:111]
	v_mfma_f32_16x16x32_bf16 v[104:107], v[178:181], v[202:205], v[104:107]
	v_mfma_f32_16x16x32_bf16 v[100:103], v[170:173], v[210:213], v[100:103]
	v_mfma_f32_16x16x32_bf16 v[96:99], v[178:181], v[210:213], v[96:99]
	v_mfma_f32_16x16x32_bf16 v[124:127], v[174:177], v[190:193], v[124:127]
	v_mfma_f32_16x16x32_bf16 v[120:123], v[182:185], v[190:193], v[120:123]
	v_mfma_f32_16x16x32_bf16 v[116:119], v[174:177], v[198:201], v[116:119]
	v_mfma_f32_16x16x32_bf16 v[112:115], v[182:185], v[198:201], v[112:115]
	v_mfma_f32_16x16x32_bf16 v[108:111], v[174:177], v[206:209], v[108:111]
	v_mfma_f32_16x16x32_bf16 v[104:107], v[182:185], v[206:209], v[104:107]
	v_mfma_f32_16x16x32_bf16 v[100:103], v[174:177], v[214:217], v[100:103]
	v_mfma_f32_16x16x32_bf16 v[96:99], v[182:185], v[214:217], v[96:99]
	s_barrier
	s_add_u32 s98, s42, 0x80
	s_addc_u32 s99, s43, 0
	s_add_u32 s100, s44, 0x80
	s_addc_u32 s101, s45, 0
	s_add_i32 s75, s65, s53
	s_mov_b32 m0, s75
	ds_read_b128 v[186:189], v161 offset:16384
	ds_read_b128 v[190:193], v161 offset:17408
	ds_read_b128 v[194:197], v161 offset:18432
	ds_read_b128 v[198:201], v161 offset:19456
	ds_read_b128 v[202:205], v161 offset:20480
	ds_read_b128 v[206:209], v161 offset:21504
	ds_read_b128 v[210:213], v161 offset:22528
	ds_read_b128 v[214:217], v161 offset:23552
	global_load_lds_dwordx4 v132, s[42:43]
	s_add_i32 m0, s75, 0x2000
	s_add_u32 s76, s42, 0x100000
	s_addc_u32 s77, s43, 0
	s_add_i32 s75, s66, s53
	global_load_lds_dwordx4 v128, s[42:43]
	s_mov_b32 m0, s75
	s_nop 0
	global_load_lds_dwordx4 v132, s[76:77]
	s_add_i32 m0, s75, 0x2000
	s_nop 0
	global_load_lds_dwordx4 v128, s[76:77]
	s_mov_b32 m0, s55
	s_nop 0
	global_load_lds_dwordx4 v134, s[44:45]
	s_mov_b32 m0, s56
	s_nop 0
	global_load_lds_dwordx4 v130, s[44:45]
	s_waitcnt vmcnt(8)
	s_waitcnt lgkmcnt(0)
	s_barrier
	v_mfma_f32_16x16x32_bf16 v[32:35], v[150:153], v[186:189], v[32:35]
	v_mfma_f32_16x16x32_bf16 v[28:31], v[162:165], v[186:189], v[28:31]
	v_mfma_f32_16x16x32_bf16 v[20:23], v[150:153], v[194:197], v[20:23]
	v_mfma_f32_16x16x32_bf16 v[16:19], v[162:165], v[194:197], v[16:19]
	v_mfma_f32_16x16x32_bf16 v[12:15], v[150:153], v[202:205], v[12:15]
	v_mfma_f32_16x16x32_bf16 v[8:11], v[162:165], v[202:205], v[8:11]
	v_mfma_f32_16x16x32_bf16 v[4:7], v[150:153], v[210:213], v[4:7]
	v_mfma_f32_16x16x32_bf16 v[0:3], v[162:165], v[210:213], v[0:3]
	v_mfma_f32_16x16x32_bf16 v[32:35], v[154:157], v[190:193], v[32:35]
	v_mfma_f32_16x16x32_bf16 v[28:31], v[166:169], v[190:193], v[28:31]
	v_mfma_f32_16x16x32_bf16 v[20:23], v[154:157], v[198:201], v[20:23]
	v_mfma_f32_16x16x32_bf16 v[16:19], v[166:169], v[198:201], v[16:19]
	v_mfma_f32_16x16x32_bf16 v[12:15], v[154:157], v[206:209], v[12:15]
	v_mfma_f32_16x16x32_bf16 v[8:11], v[166:169], v[206:209], v[8:11]
	v_mfma_f32_16x16x32_bf16 v[4:7], v[154:157], v[214:217], v[4:7]
	v_mfma_f32_16x16x32_bf16 v[0:3], v[166:169], v[214:217], v[0:3]
	v_mfma_f32_16x16x32_bf16 v[72:75], v[170:173], v[186:189], v[72:75]
	v_mfma_f32_16x16x32_bf16 v[64:67], v[178:181], v[186:189], v[64:67]
	v_mfma_f32_16x16x32_bf16 v[52:55], v[170:173], v[194:197], v[52:55]
	v_mfma_f32_16x16x32_bf16 v[48:51], v[178:181], v[194:197], v[48:51]
	v_mfma_f32_16x16x32_bf16 v[44:47], v[170:173], v[202:205], v[44:47]
	v_mfma_f32_16x16x32_bf16 v[40:43], v[178:181], v[202:205], v[40:43]
	v_mfma_f32_16x16x32_bf16 v[36:39], v[170:173], v[210:213], v[36:39]
	v_mfma_f32_16x16x32_bf16 v[24:27], v[178:181], v[210:213], v[24:27]
	v_mfma_f32_16x16x32_bf16 v[72:75], v[174:177], v[190:193], v[72:75]
	v_mfma_f32_16x16x32_bf16 v[64:67], v[182:185], v[190:193], v[64:67]
	v_mfma_f32_16x16x32_bf16 v[52:55], v[174:177], v[198:201], v[52:55]
	v_mfma_f32_16x16x32_bf16 v[48:51], v[182:185], v[198:201], v[48:51]
	v_mfma_f32_16x16x32_bf16 v[44:47], v[174:177], v[206:209], v[44:47]
	v_mfma_f32_16x16x32_bf16 v[40:43], v[182:185], v[206:209], v[40:43]
	v_mfma_f32_16x16x32_bf16 v[36:39], v[174:177], v[214:217], v[36:39]
	v_mfma_f32_16x16x32_bf16 v[24:27], v[182:185], v[214:217], v[24:27]
	s_barrier
	s_add_i32 s75, 0, 0x18000
	v_add_u32_e32 v136, s75, v158
	s_add_i32 s76, 0, 0x1c000
	ds_read_b128 v[150:153], v136
	ds_read_b128 v[154:157], v136 offset:1024
	ds_read_b128 v[162:165], v136 offset:2048
	ds_read_b128 v[166:169], v136 offset:3072
	v_add_u32_e32 v136, s76, v158
	ds_read_b128 v[170:173], v136
	ds_read_b128 v[174:177], v136 offset:1024
	ds_read_b128 v[178:181], v136 offset:2048
	ds_read_b128 v[182:185], v136 offset:3072
	s_add_u32 s44, s44, 0x100000
	s_addc_u32 s45, s45, 0
	s_mov_b32 m0, s57
	ds_read_b128 v[186:189], v161 offset:32768
	ds_read_b128 v[190:193], v161 offset:33792
	ds_read_b128 v[194:197], v161 offset:34816
	ds_read_b128 v[198:201], v161 offset:35840
	ds_read_b128 v[202:205], v161 offset:36864
	ds_read_b128 v[206:209], v161 offset:37888
	ds_read_b128 v[210:213], v161 offset:38912
	ds_read_b128 v[214:217], v161 offset:39936
	global_load_lds_dwordx4 v134, s[44:45]
	s_mov_b32 m0, s58
	s_nop 0
	global_load_lds_dwordx4 v130, s[44:45]
	s_waitcnt vmcnt(8)
	s_waitcnt lgkmcnt(0)
	s_barrier
	v_mfma_f32_16x16x32_bf16 v[92:95], v[150:153], v[186:189], v[92:95]
	v_mfma_f32_16x16x32_bf16 v[88:91], v[162:165], v[186:189], v[88:91]
	v_mfma_f32_16x16x32_bf16 v[84:87], v[150:153], v[194:197], v[84:87]
	v_mfma_f32_16x16x32_bf16 v[80:83], v[162:165], v[194:197], v[80:83]
	v_mfma_f32_16x16x32_bf16 v[76:79], v[150:153], v[202:205], v[76:79]
	v_mfma_f32_16x16x32_bf16 v[68:71], v[162:165], v[202:205], v[68:71]
	v_mfma_f32_16x16x32_bf16 v[60:63], v[150:153], v[210:213], v[60:63]
	v_mfma_f32_16x16x32_bf16 v[56:59], v[162:165], v[210:213], v[56:59]
	v_mfma_f32_16x16x32_bf16 v[92:95], v[154:157], v[190:193], v[92:95]
	v_mfma_f32_16x16x32_bf16 v[88:91], v[166:169], v[190:193], v[88:91]
	v_mfma_f32_16x16x32_bf16 v[84:87], v[154:157], v[198:201], v[84:87]
	v_mfma_f32_16x16x32_bf16 v[80:83], v[166:169], v[198:201], v[80:83]
	v_mfma_f32_16x16x32_bf16 v[76:79], v[154:157], v[206:209], v[76:79]
	v_mfma_f32_16x16x32_bf16 v[68:71], v[166:169], v[206:209], v[68:71]
	v_mfma_f32_16x16x32_bf16 v[60:63], v[154:157], v[214:217], v[60:63]
	v_mfma_f32_16x16x32_bf16 v[56:59], v[166:169], v[214:217], v[56:59]
	v_mfma_f32_16x16x32_bf16 v[124:127], v[170:173], v[186:189], v[124:127]
	v_mfma_f32_16x16x32_bf16 v[120:123], v[178:181], v[186:189], v[120:123]
	v_mfma_f32_16x16x32_bf16 v[116:119], v[170:173], v[194:197], v[116:119]
	v_mfma_f32_16x16x32_bf16 v[112:115], v[178:181], v[194:197], v[112:115]
	v_mfma_f32_16x16x32_bf16 v[108:111], v[170:173], v[202:205], v[108:111]
	v_mfma_f32_16x16x32_bf16 v[104:107], v[178:181], v[202:205], v[104:107]
	v_mfma_f32_16x16x32_bf16 v[100:103], v[170:173], v[210:213], v[100:103]
	v_mfma_f32_16x16x32_bf16 v[96:99], v[178:181], v[210:213], v[96:99]
	v_mfma_f32_16x16x32_bf16 v[124:127], v[174:177], v[190:193], v[124:127]
	v_mfma_f32_16x16x32_bf16 v[120:123], v[182:185], v[190:193], v[120:123]
	v_mfma_f32_16x16x32_bf16 v[116:119], v[174:177], v[198:201], v[116:119]
	v_mfma_f32_16x16x32_bf16 v[112:115], v[182:185], v[198:201], v[112:115]
	v_mfma_f32_16x16x32_bf16 v[108:111], v[174:177], v[206:209], v[108:111]
	v_mfma_f32_16x16x32_bf16 v[104:107], v[182:185], v[206:209], v[104:107]
	v_mfma_f32_16x16x32_bf16 v[100:103], v[174:177], v[214:217], v[100:103]
	v_mfma_f32_16x16x32_bf16 v[96:99], v[182:185], v[214:217], v[96:99]
	s_barrier
	s_add_i32 s44, s75, s53
	s_mov_b32 m0, s44
	ds_read_b128 v[186:189], v161 offset:49152
	ds_read_b128 v[190:193], v161 offset:50176
	ds_read_b128 v[194:197], v161 offset:51200
	ds_read_b128 v[198:201], v161 offset:52224
	ds_read_b128 v[202:205], v161 offset:53248
	ds_read_b128 v[206:209], v161 offset:54272
	ds_read_b128 v[210:213], v161 offset:55296
	ds_read_b128 v[214:217], v161 offset:56320
	global_load_lds_dwordx4 v132, s[98:99]
	s_add_i32 m0, s44, 0x2000
	s_add_u32 s42, s42, 0x100080
	s_addc_u32 s43, s43, 0
	s_add_i32 s44, s76, s53
	global_load_lds_dwordx4 v128, s[98:99]
	s_mov_b32 m0, s44
	s_nop 0
	global_load_lds_dwordx4 v132, s[42:43]
	s_add_i32 m0, s44, 0x2000
	s_nop 0
	global_load_lds_dwordx4 v128, s[42:43]
	s_mov_b32 m0, s62
	s_nop 0
	global_load_lds_dwordx4 v134, s[100:101]
	s_mov_b32 m0, s63
	s_nop 0
	global_load_lds_dwordx4 v130, s[100:101]
	s_waitcnt vmcnt(8)
	s_waitcnt lgkmcnt(0)
	s_barrier
	v_mfma_f32_16x16x32_bf16 v[32:35], v[150:153], v[186:189], v[32:35]
	v_mfma_f32_16x16x32_bf16 v[28:31], v[162:165], v[186:189], v[28:31]
	v_mfma_f32_16x16x32_bf16 v[20:23], v[150:153], v[194:197], v[20:23]
	v_mfma_f32_16x16x32_bf16 v[16:19], v[162:165], v[194:197], v[16:19]
	v_mfma_f32_16x16x32_bf16 v[12:15], v[150:153], v[202:205], v[12:15]
	v_mfma_f32_16x16x32_bf16 v[8:11], v[162:165], v[202:205], v[8:11]
	v_mfma_f32_16x16x32_bf16 v[4:7], v[150:153], v[210:213], v[4:7]
	v_mfma_f32_16x16x32_bf16 v[0:3], v[162:165], v[210:213], v[0:3]
	v_mfma_f32_16x16x32_bf16 v[32:35], v[154:157], v[190:193], v[32:35]
	v_mfma_f32_16x16x32_bf16 v[28:31], v[166:169], v[190:193], v[28:31]
	v_mfma_f32_16x16x32_bf16 v[20:23], v[154:157], v[198:201], v[20:23]
	v_mfma_f32_16x16x32_bf16 v[16:19], v[166:169], v[198:201], v[16:19]
	v_mfma_f32_16x16x32_bf16 v[12:15], v[154:157], v[206:209], v[12:15]
	v_mfma_f32_16x16x32_bf16 v[8:11], v[166:169], v[206:209], v[8:11]
	v_mfma_f32_16x16x32_bf16 v[4:7], v[154:157], v[214:217], v[4:7]
	v_mfma_f32_16x16x32_bf16 v[0:3], v[166:169], v[214:217], v[0:3]
	v_mfma_f32_16x16x32_bf16 v[72:75], v[170:173], v[186:189], v[72:75]
	v_mfma_f32_16x16x32_bf16 v[64:67], v[178:181], v[186:189], v[64:67]
	v_mfma_f32_16x16x32_bf16 v[52:55], v[170:173], v[194:197], v[52:55]
	v_mfma_f32_16x16x32_bf16 v[48:51], v[178:181], v[194:197], v[48:51]
	v_mfma_f32_16x16x32_bf16 v[44:47], v[170:173], v[202:205], v[44:47]
	v_mfma_f32_16x16x32_bf16 v[40:43], v[178:181], v[202:205], v[40:43]
	v_mfma_f32_16x16x32_bf16 v[36:39], v[170:173], v[210:213], v[36:39]
	v_mfma_f32_16x16x32_bf16 v[24:27], v[178:181], v[210:213], v[24:27]
	v_mfma_f32_16x16x32_bf16 v[72:75], v[174:177], v[190:193], v[72:75]
	v_mfma_f32_16x16x32_bf16 v[64:67], v[182:185], v[190:193], v[64:67]
	v_mfma_f32_16x16x32_bf16 v[52:55], v[174:177], v[198:201], v[52:55]
	v_mfma_f32_16x16x32_bf16 v[48:51], v[182:185], v[198:201], v[48:51]
	v_mfma_f32_16x16x32_bf16 v[44:47], v[174:177], v[206:209], v[44:47]
	v_mfma_f32_16x16x32_bf16 v[40:43], v[182:185], v[206:209], v[40:43]
	v_mfma_f32_16x16x32_bf16 v[36:39], v[174:177], v[214:217], v[36:39]
	v_mfma_f32_16x16x32_bf16 v[24:27], v[182:185], v[214:217], v[24:27]
	s_barrier
	s_add_i32 s74, s74, 2
	s_add_u32 s72, s72, 0x100
	s_addc_u32 s73, s73, 0
	s_add_u32 s40, s40, 0x100
	s_addc_u32 s41, s41, 0
	s_cmp_gt_u32 s74, 61
	s_cbranch_scc0 .LBB0_432
	s_and_b64 vcc, exec, s[14:15]
	s_cbranch_vccz .LBB0_436
	s_barrier
	v_lshl_add_u32 v150, s12, 8, v139
	s_cmp_lg_u32 s69, 54
	s_mov_b64 s[40:41], -1
	s_cbranch_scc1 .LBB0_437

.LBB0_1612:
	ds_read_b128 v[144:147], v151
	ds_read_b128 v[156:159], v151 offset:1024
	ds_read_b128 v[160:163], v151 offset:2048
	ds_read_b128 v[164:167], v151 offset:3072
	ds_read_b128 v[168:171], v152
	ds_read_b128 v[172:175], v152 offset:1024
	ds_read_b128 v[176:179], v152 offset:2048
	ds_read_b128 v[180:183], v152 offset:3072
	s_add_u32 s34, s30, 0xfff00080
	s_addc_u32 s35, s31, -1
	s_cmp_eq_u32 s59, 60
	s_cselect_b32 s37, s25, s35
	s_cselect_b32 s36, s55, s34
	s_cselect_b32 s35, s23, s58
	s_cselect_b32 s34, s56, s57
	s_add_i32 m0, s9, 0xc000
	ds_read_b128 v[184:187], v153
	ds_read_b128 v[188:191], v153 offset:1024
	ds_read_b128 v[192:195], v153 offset:2048
	ds_read_b128 v[196:199], v153 offset:3072
	ds_read_b128 v[200:203], v153 offset:4096
	ds_read_b128 v[204:207], v153 offset:5120
	ds_read_b128 v[208:211], v153 offset:6144
	ds_read_b128 v[212:215], v153 offset:7168
	global_load_lds_dwordx4 v138, s[30:31]
	s_add_i32 m0, s9, 0xe000
	s_nop 0
	global_load_lds_dwordx4 v136, s[30:31]
	s_waitcnt vmcnt(8)
	s_waitcnt lgkmcnt(0)
	s_barrier
	v_mfma_f32_16x16x32_bf16 v[124:127], v[144:147], v[184:187], v[124:127]
	v_mfma_f32_16x16x32_bf16 v[120:123], v[160:163], v[184:187], v[120:123]
	v_mfma_f32_16x16x32_bf16 v[108:111], v[144:147], v[192:195], v[108:111]
	v_mfma_f32_16x16x32_bf16 v[104:107], v[160:163], v[192:195], v[104:107]
	v_mfma_f32_16x16x32_bf16 v[92:95], v[144:147], v[200:203], v[92:95]
	v_mfma_f32_16x16x32_bf16 v[88:91], v[160:163], v[200:203], v[88:91]
	v_mfma_f32_16x16x32_bf16 v[76:79], v[144:147], v[208:211], v[76:79]
	v_mfma_f32_16x16x32_bf16 v[72:75], v[160:163], v[208:211], v[72:75]
	v_mfma_f32_16x16x32_bf16 v[124:127], v[156:159], v[188:191], v[124:127]
	v_mfma_f32_16x16x32_bf16 v[120:123], v[164:167], v[188:191], v[120:123]
	v_mfma_f32_16x16x32_bf16 v[108:111], v[156:159], v[196:199], v[108:111]
	v_mfma_f32_16x16x32_bf16 v[104:107], v[164:167], v[196:199], v[104:107]
	v_mfma_f32_16x16x32_bf16 v[92:95], v[156:159], v[204:207], v[92:95]
	v_mfma_f32_16x16x32_bf16 v[88:91], v[164:167], v[204:207], v[88:91]
	v_mfma_f32_16x16x32_bf16 v[76:79], v[156:159], v[212:215], v[76:79]
	v_mfma_f32_16x16x32_bf16 v[72:75], v[164:167], v[212:215], v[72:75]
	v_mfma_f32_16x16x32_bf16 v[116:119], v[168:171], v[184:187], v[116:119]
	v_mfma_f32_16x16x32_bf16 v[112:115], v[176:179], v[184:187], v[112:115]
	v_mfma_f32_16x16x32_bf16 v[100:103], v[168:171], v[192:195], v[100:103]
	v_mfma_f32_16x16x32_bf16 v[96:99], v[176:179], v[192:195], v[96:99]
	v_mfma_f32_16x16x32_bf16 v[84:87], v[168:171], v[200:203], v[84:87]
	v_mfma_f32_16x16x32_bf16 v[80:83], v[176:179], v[200:203], v[80:83]
	v_mfma_f32_16x16x32_bf16 v[68:71], v[168:171], v[208:211], v[68:71]
	v_mfma_f32_16x16x32_bf16 v[64:67], v[176:179], v[208:211], v[64:67]
	v_mfma_f32_16x16x32_bf16 v[116:119], v[172:175], v[188:191], v[116:119]
	v_mfma_f32_16x16x32_bf16 v[112:115], v[180:183], v[188:191], v[112:115]
	v_mfma_f32_16x16x32_bf16 v[100:103], v[172:175], v[196:199], v[100:103]
	v_mfma_f32_16x16x32_bf16 v[96:99], v[180:183], v[196:199], v[96:99]
	v_mfma_f32_16x16x32_bf16 v[84:87], v[172:175], v[204:207], v[84:87]
	v_mfma_f32_16x16x32_bf16 v[80:83], v[180:183], v[204:207], v[80:83]
	v_mfma_f32_16x16x32_bf16 v[68:71], v[172:175], v[212:215], v[68:71]
	v_mfma_f32_16x16x32_bf16 v[64:67], v[180:183], v[212:215], v[64:67]
	s_barrier
	s_add_u32 s98, s34, 0x80
	s_addc_u32 s99, s35, 0
	s_add_u32 s100, s36, 0x80
	s_addc_u32 s101, s37, 0
	s_add_i32 s60, s52, s45
	s_mov_b32 m0, s60
	ds_read_b128 v[184:187], v153 offset:16384
	ds_read_b128 v[188:191], v153 offset:17408
	ds_read_b128 v[192:195], v153 offset:18432
	ds_read_b128 v[196:199], v153 offset:19456
	ds_read_b128 v[200:203], v153 offset:20480
	ds_read_b128 v[204:207], v153 offset:21504
	ds_read_b128 v[208:211], v153 offset:22528
	ds_read_b128 v[212:215], v153 offset:23552
	global_load_lds_dwordx4 v130, s[34:35]
	s_add_i32 m0, s60, 0x2000
	s_add_u32 s60, s34, 0x100000
	s_addc_u32 s61, s35, 0
	s_add_i32 s62, s53, s45
	global_load_lds_dwordx4 v134, s[34:35]
	s_mov_b32 m0, s62
	s_nop 0
	global_load_lds_dwordx4 v130, s[60:61]
	s_add_i32 m0, s62, 0x2000
	s_nop 0
	global_load_lds_dwordx4 v134, s[60:61]
	s_mov_b32 m0, s9
	s_nop 0
	global_load_lds_dwordx4 v128, s[36:37]
	s_mov_b32 m0, s46
	s_nop 0
	global_load_lds_dwordx4 v132, s[36:37]
	s_waitcnt vmcnt(8)
	s_waitcnt lgkmcnt(0)
	s_barrier
	v_mfma_f32_16x16x32_bf16 v[60:63], v[144:147], v[184:187], v[60:63]
	v_mfma_f32_16x16x32_bf16 v[56:59], v[160:163], v[184:187], v[56:59]
	v_mfma_f32_16x16x32_bf16 v[44:47], v[144:147], v[192:195], v[44:47]
	v_mfma_f32_16x16x32_bf16 v[40:43], v[160:163], v[192:195], v[40:43]
	v_mfma_f32_16x16x32_bf16 v[28:31], v[144:147], v[200:203], v[28:31]
	v_mfma_f32_16x16x32_bf16 v[24:27], v[160:163], v[200:203], v[24:27]
	v_mfma_f32_16x16x32_bf16 v[12:15], v[144:147], v[208:211], v[12:15]
	v_mfma_f32_16x16x32_bf16 v[8:11], v[160:163], v[208:211], v[8:11]
	v_mfma_f32_16x16x32_bf16 v[60:63], v[156:159], v[188:191], v[60:63]
	v_mfma_f32_16x16x32_bf16 v[56:59], v[164:167], v[188:191], v[56:59]
	v_mfma_f32_16x16x32_bf16 v[44:47], v[156:159], v[196:199], v[44:47]
	v_mfma_f32_16x16x32_bf16 v[40:43], v[164:167], v[196:199], v[40:43]
	v_mfma_f32_16x16x32_bf16 v[28:31], v[156:159], v[204:207], v[28:31]
	v_mfma_f32_16x16x32_bf16 v[24:27], v[164:167], v[204:207], v[24:27]
	v_mfma_f32_16x16x32_bf16 v[12:15], v[156:159], v[212:215], v[12:15]
	v_mfma_f32_16x16x32_bf16 v[8:11], v[164:167], v[212:215], v[8:11]
	v_mfma_f32_16x16x32_bf16 v[52:55], v[168:171], v[184:187], v[52:55]
	v_mfma_f32_16x16x32_bf16 v[48:51], v[176:179], v[184:187], v[48:51]
	v_mfma_f32_16x16x32_bf16 v[36:39], v[168:171], v[192:195], v[36:39]
	v_mfma_f32_16x16x32_bf16 v[32:35], v[176:179], v[192:195], v[32:35]
	v_mfma_f32_16x16x32_bf16 v[20:23], v[168:171], v[200:203], v[20:23]
	v_mfma_f32_16x16x32_bf16 v[16:19], v[176:179], v[200:203], v[16:19]
	v_mfma_f32_16x16x32_bf16 v[4:7], v[168:171], v[208:211], v[4:7]
	v_mfma_f32_16x16x32_bf16 v[0:3], v[176:179], v[208:211], v[0:3]
	v_mfma_f32_16x16x32_bf16 v[52:55], v[172:175], v[188:191], v[52:55]
	v_mfma_f32_16x16x32_bf16 v[48:51], v[180:183], v[188:191], v[48:51]
	v_mfma_f32_16x16x32_bf16 v[36:39], v[172:175], v[196:199], v[36:39]
	v_mfma_f32_16x16x32_bf16 v[32:35], v[180:183], v[196:199], v[32:35]
	v_mfma_f32_16x16x32_bf16 v[20:23], v[172:175], v[204:207], v[20:23]
	v_mfma_f32_16x16x32_bf16 v[16:19], v[180:183], v[204:207], v[16:19]
	v_mfma_f32_16x16x32_bf16 v[4:7], v[172:175], v[212:215], v[4:7]
	v_mfma_f32_16x16x32_bf16 v[0:3], v[180:183], v[212:215], v[0:3]
	s_barrier
	s_add_i32 s60, 0, 0x18000
	v_add_u32_e32 v155, s60, v149
	s_add_i32 s61, 0, 0x1c000
	ds_read_b128 v[144:147], v155
	ds_read_b128 v[156:159], v155 offset:1024
	ds_read_b128 v[160:163], v155 offset:2048
	ds_read_b128 v[164:167], v155 offset:3072
	v_add_u32_e32 v155, s61, v149
	ds_read_b128 v[168:171], v155
	ds_read_b128 v[172:175], v155 offset:1024
	ds_read_b128 v[176:179], v155 offset:2048
	ds_read_b128 v[180:183], v155 offset:3072
	s_add_u32 s36, s36, 0x100000
	s_addc_u32 s37, s37, 0
	s_mov_b32 m0, s47
	ds_read_b128 v[184:187], v153 offset:32768
	ds_read_b128 v[188:191], v153 offset:33792
	ds_read_b128 v[192:195], v153 offset:34816
	ds_read_b128 v[196:199], v153 offset:35840
	ds_read_b128 v[200:203], v153 offset:36864
	ds_read_b128 v[204:207], v153 offset:37888
	ds_read_b128 v[208:211], v153 offset:38912
	ds_read_b128 v[212:215], v153 offset:39936
	global_load_lds_dwordx4 v128, s[36:37]
	s_mov_b32 m0, s48
	s_nop 0
	global_load_lds_dwordx4 v132, s[36:37]
	s_waitcnt vmcnt(8)
	s_waitcnt lgkmcnt(0)
	s_barrier
	v_mfma_f32_16x16x32_bf16 v[124:127], v[144:147], v[184:187], v[124:127]
	v_mfma_f32_16x16x32_bf16 v[120:123], v[160:163], v[184:187], v[120:123]
	v_mfma_f32_16x16x32_bf16 v[108:111], v[144:147], v[192:195], v[108:111]
	v_mfma_f32_16x16x32_bf16 v[104:107], v[160:163], v[192:195], v[104:107]
	v_mfma_f32_16x16x32_bf16 v[92:95], v[144:147], v[200:203], v[92:95]
	v_mfma_f32_16x16x32_bf16 v[88:91], v[160:163], v[200:203], v[88:91]
	v_mfma_f32_16x16x32_bf16 v[76:79], v[144:147], v[208:211], v[76:79]
	v_mfma_f32_16x16x32_bf16 v[72:75], v[160:163], v[208:211], v[72:75]
	v_mfma_f32_16x16x32_bf16 v[124:127], v[156:159], v[188:191], v[124:127]
	v_mfma_f32_16x16x32_bf16 v[120:123], v[164:167], v[188:191], v[120:123]
	v_mfma_f32_16x16x32_bf16 v[108:111], v[156:159], v[196:199], v[108:111]
	v_mfma_f32_16x16x32_bf16 v[104:107], v[164:167], v[196:199], v[104:107]
	v_mfma_f32_16x16x32_bf16 v[92:95], v[156:159], v[204:207], v[92:95]
	v_mfma_f32_16x16x32_bf16 v[88:91], v[164:167], v[204:207], v[88:91]
	v_mfma_f32_16x16x32_bf16 v[76:79], v[156:159], v[212:215], v[76:79]
	v_mfma_f32_16x16x32_bf16 v[72:75], v[164:167], v[212:215], v[72:75]
	v_mfma_f32_16x16x32_bf16 v[116:119], v[168:171], v[184:187], v[116:119]
	v_mfma_f32_16x16x32_bf16 v[112:115], v[176:179], v[184:187], v[112:115]
	v_mfma_f32_16x16x32_bf16 v[100:103], v[168:171], v[192:195], v[100:103]
	v_mfma_f32_16x16x32_bf16 v[96:99], v[176:179], v[192:195], v[96:99]
	v_mfma_f32_16x16x32_bf16 v[84:87], v[168:171], v[200:203], v[84:87]
	v_mfma_f32_16x16x32_bf16 v[80:83], v[176:179], v[200:203], v[80:83]
	v_mfma_f32_16x16x32_bf16 v[68:71], v[168:171], v[208:211], v[68:71]
	v_mfma_f32_16x16x32_bf16 v[64:67], v[176:179], v[208:211], v[64:67]
	v_mfma_f32_16x16x32_bf16 v[116:119], v[172:175], v[188:191], v[116:119]
	v_mfma_f32_16x16x32_bf16 v[112:115], v[180:183], v[188:191], v[112:115]
	v_mfma_f32_16x16x32_bf16 v[100:103], v[172:175], v[196:199], v[100:103]
	v_mfma_f32_16x16x32_bf16 v[96:99], v[180:183], v[196:199], v[96:99]
	v_mfma_f32_16x16x32_bf16 v[84:87], v[172:175], v[204:207], v[84:87]
	v_mfma_f32_16x16x32_bf16 v[80:83], v[180:183], v[204:207], v[80:83]
	v_mfma_f32_16x16x32_bf16 v[68:71], v[172:175], v[212:215], v[68:71]
	v_mfma_f32_16x16x32_bf16 v[64:67], v[180:183], v[212:215], v[64:67]
	s_barrier
	s_add_i32 s36, s60, s45
	s_mov_b32 m0, s36
	ds_read_b128 v[184:187], v153 offset:49152
	ds_read_b128 v[188:191], v153 offset:50176
	ds_read_b128 v[192:195], v153 offset:51200
	ds_read_b128 v[196:199], v153 offset:52224
	ds_read_b128 v[200:203], v153 offset:53248
	ds_read_b128 v[204:207], v153 offset:54272
	ds_read_b128 v[208:211], v153 offset:55296
	ds_read_b128 v[212:215], v153 offset:56320
	global_load_lds_dwordx4 v130, s[98:99]
	s_add_i32 m0, s36, 0x2000
	s_add_u32 s34, s34, 0x100080
	s_addc_u32 s35, s35, 0
	s_add_i32 s36, s61, s45
	global_load_lds_dwordx4 v134, s[98:99]
	s_mov_b32 m0, s36
	s_nop 0
	global_load_lds_dwordx4 v130, s[34:35]
	s_add_i32 m0, s36, 0x2000
	s_nop 0
	global_load_lds_dwordx4 v134, s[34:35]
	s_mov_b32 m0, s50
	s_nop 0
	global_load_lds_dwordx4 v128, s[100:101]
	s_mov_b32 m0, s51
	s_nop 0
	global_load_lds_dwordx4 v132, s[100:101]
	s_waitcnt vmcnt(8)
	s_waitcnt lgkmcnt(0)
	s_barrier
	v_mfma_f32_16x16x32_bf16 v[60:63], v[144:147], v[184:187], v[60:63]
	v_mfma_f32_16x16x32_bf16 v[56:59], v[160:163], v[184:187], v[56:59]
	v_mfma_f32_16x16x32_bf16 v[44:47], v[144:147], v[192:195], v[44:47]
	v_mfma_f32_16x16x32_bf16 v[40:43], v[160:163], v[192:195], v[40:43]
	v_mfma_f32_16x16x32_bf16 v[28:31], v[144:147], v[200:203], v[28:31]
	v_mfma_f32_16x16x32_bf16 v[24:27], v[160:163], v[200:203], v[24:27]
	v_mfma_f32_16x16x32_bf16 v[12:15], v[144:147], v[208:211], v[12:15]
	v_mfma_f32_16x16x32_bf16 v[8:11], v[160:163], v[208:211], v[8:11]
	v_mfma_f32_16x16x32_bf16 v[60:63], v[156:159], v[188:191], v[60:63]
	v_mfma_f32_16x16x32_bf16 v[56:59], v[164:167], v[188:191], v[56:59]
	v_mfma_f32_16x16x32_bf16 v[44:47], v[156:159], v[196:199], v[44:47]
	v_mfma_f32_16x16x32_bf16 v[40:43], v[164:167], v[196:199], v[40:43]
	v_mfma_f32_16x16x32_bf16 v[28:31], v[156:159], v[204:207], v[28:31]
	v_mfma_f32_16x16x32_bf16 v[24:27], v[164:167], v[204:207], v[24:27]
	v_mfma_f32_16x16x32_bf16 v[12:15], v[156:159], v[212:215], v[12:15]
	v_mfma_f32_16x16x32_bf16 v[8:11], v[164:167], v[212:215], v[8:11]
	v_mfma_f32_16x16x32_bf16 v[52:55], v[168:171], v[184:187], v[52:55]
	v_mfma_f32_16x16x32_bf16 v[48:51], v[176:179], v[184:187], v[48:51]
	v_mfma_f32_16x16x32_bf16 v[36:39], v[168:171], v[192:195], v[36:39]
	v_mfma_f32_16x16x32_bf16 v[32:35], v[176:179], v[192:195], v[32:35]
	v_mfma_f32_16x16x32_bf16 v[20:23], v[168:171], v[200:203], v[20:23]
	v_mfma_f32_16x16x32_bf16 v[16:19], v[176:179], v[200:203], v[16:19]
	v_mfma_f32_16x16x32_bf16 v[4:7], v[168:171], v[208:211], v[4:7]
	v_mfma_f32_16x16x32_bf16 v[0:3], v[176:179], v[208:211], v[0:3]
	v_mfma_f32_16x16x32_bf16 v[52:55], v[172:175], v[188:191], v[52:55]
	v_mfma_f32_16x16x32_bf16 v[48:51], v[180:183], v[188:191], v[48:51]
	v_mfma_f32_16x16x32_bf16 v[36:39], v[172:175], v[196:199], v[36:39]
	v_mfma_f32_16x16x32_bf16 v[32:35], v[180:183], v[196:199], v[32:35]
	v_mfma_f32_16x16x32_bf16 v[20:23], v[172:175], v[204:207], v[20:23]
	v_mfma_f32_16x16x32_bf16 v[16:19], v[180:183], v[204:207], v[16:19]
	v_mfma_f32_16x16x32_bf16 v[4:7], v[172:175], v[212:215], v[4:7]
	v_mfma_f32_16x16x32_bf16 v[0:3], v[180:183], v[212:215], v[0:3]
	s_barrier
	s_add_i32 s59, s59, 2
	s_add_u32 s57, s57, 0x100
	s_addc_u32 s58, s58, 0
	s_add_u32 s30, s30, 0x100
	s_addc_u32 s31, s31, 0
	s_cmp_gt_u32 s59, 61
	s_cbranch_scc0 .LBB0_1612
	s_and_b64 vcc, exec, s[20:21]
	s_cbranch_vccz .LBB0_1615
	s_barrier

.LBB0_1758:
	ds_read_b128 v[150:153], v147
	ds_read_b128 v[154:157], v147 offset:1024
	ds_read_b128 v[158:161], v147 offset:2048
	ds_read_b128 v[162:165], v147 offset:3072
	ds_read_b128 v[166:169], v148
	ds_read_b128 v[170:173], v148 offset:1024
	ds_read_b128 v[174:177], v148 offset:2048
	ds_read_b128 v[178:181], v148 offset:3072
	s_add_u32 s26, s24, 0xfff00080
	s_addc_u32 s27, s25, -1
	s_cmp_eq_u32 s55, 60
	s_cselect_b32 s29, s17, s27
	s_cselect_b32 s28, s51, s26
	s_cselect_b32 s27, s15, s54
	s_cselect_b32 s26, s52, s53
	s_add_i32 m0, s23, 0xc000
	ds_read_b128 v[182:185], v149
	ds_read_b128 v[186:189], v149 offset:1024
	ds_read_b128 v[190:193], v149 offset:2048
	ds_read_b128 v[194:197], v149 offset:3072
	ds_read_b128 v[198:201], v149 offset:4096
	ds_read_b128 v[202:205], v149 offset:5120
	ds_read_b128 v[206:209], v149 offset:6144
	ds_read_b128 v[210:213], v149 offset:7168
	global_load_lds_dwordx4 v138, s[24:25]
	s_add_i32 m0, s23, 0xe000
	s_nop 0
	global_load_lds_dwordx4 v136, s[24:25]
	s_waitcnt vmcnt(8)
	s_waitcnt lgkmcnt(0)
	s_barrier
	v_mfma_f32_16x16x32_bf16 v[124:127], v[150:153], v[182:185], v[124:127]
	v_mfma_f32_16x16x32_bf16 v[120:123], v[158:161], v[182:185], v[120:123]
	v_mfma_f32_16x16x32_bf16 v[108:111], v[150:153], v[190:193], v[108:111]
	v_mfma_f32_16x16x32_bf16 v[104:107], v[158:161], v[190:193], v[104:107]
	v_mfma_f32_16x16x32_bf16 v[92:95], v[150:153], v[198:201], v[92:95]
	v_mfma_f32_16x16x32_bf16 v[88:91], v[158:161], v[198:201], v[88:91]
	v_mfma_f32_16x16x32_bf16 v[76:79], v[150:153], v[206:209], v[76:79]
	v_mfma_f32_16x16x32_bf16 v[72:75], v[158:161], v[206:209], v[72:75]
	v_mfma_f32_16x16x32_bf16 v[124:127], v[154:157], v[186:189], v[124:127]
	v_mfma_f32_16x16x32_bf16 v[120:123], v[162:165], v[186:189], v[120:123]
	v_mfma_f32_16x16x32_bf16 v[108:111], v[154:157], v[194:197], v[108:111]
	v_mfma_f32_16x16x32_bf16 v[104:107], v[162:165], v[194:197], v[104:107]
	v_mfma_f32_16x16x32_bf16 v[92:95], v[154:157], v[202:205], v[92:95]
	v_mfma_f32_16x16x32_bf16 v[88:91], v[162:165], v[202:205], v[88:91]
	v_mfma_f32_16x16x32_bf16 v[76:79], v[154:157], v[210:213], v[76:79]
	v_mfma_f32_16x16x32_bf16 v[72:75], v[162:165], v[210:213], v[72:75]
	v_mfma_f32_16x16x32_bf16 v[116:119], v[166:169], v[182:185], v[116:119]
	v_mfma_f32_16x16x32_bf16 v[112:115], v[174:177], v[182:185], v[112:115]
	v_mfma_f32_16x16x32_bf16 v[100:103], v[166:169], v[190:193], v[100:103]
	v_mfma_f32_16x16x32_bf16 v[96:99], v[174:177], v[190:193], v[96:99]
	v_mfma_f32_16x16x32_bf16 v[84:87], v[166:169], v[198:201], v[84:87]
	v_mfma_f32_16x16x32_bf16 v[80:83], v[174:177], v[198:201], v[80:83]
	v_mfma_f32_16x16x32_bf16 v[68:71], v[166:169], v[206:209], v[68:71]
	v_mfma_f32_16x16x32_bf16 v[64:67], v[174:177], v[206:209], v[64:67]
	v_mfma_f32_16x16x32_bf16 v[116:119], v[170:173], v[186:189], v[116:119]
	v_mfma_f32_16x16x32_bf16 v[112:115], v[178:181], v[186:189], v[112:115]
	v_mfma_f32_16x16x32_bf16 v[100:103], v[170:173], v[194:197], v[100:103]
	v_mfma_f32_16x16x32_bf16 v[96:99], v[178:181], v[194:197], v[96:99]
	v_mfma_f32_16x16x32_bf16 v[84:87], v[170:173], v[202:205], v[84:87]
	v_mfma_f32_16x16x32_bf16 v[80:83], v[178:181], v[202:205], v[80:83]
	v_mfma_f32_16x16x32_bf16 v[68:71], v[170:173], v[210:213], v[68:71]
	v_mfma_f32_16x16x32_bf16 v[64:67], v[178:181], v[210:213], v[64:67]
	s_barrier
	s_add_u32 s98, s26, 0x80
	s_addc_u32 s99, s27, 0
	s_add_u32 s100, s28, 0x80
	s_addc_u32 s101, s29, 0
	s_add_i32 s56, s47, s39
	s_mov_b32 m0, s56
	ds_read_b128 v[182:185], v149 offset:16384
	ds_read_b128 v[186:189], v149 offset:17408
	ds_read_b128 v[190:193], v149 offset:18432
	ds_read_b128 v[194:197], v149 offset:19456
	ds_read_b128 v[198:201], v149 offset:20480
	ds_read_b128 v[202:205], v149 offset:21504
	ds_read_b128 v[206:209], v149 offset:22528
	ds_read_b128 v[210:213], v149 offset:23552
	global_load_lds_dwordx4 v132, s[26:27]
	s_add_i32 m0, s56, 0x2000
	s_add_u32 s56, s26, 0x100000
	s_addc_u32 s57, s27, 0
	s_add_i32 s58, s48, s39
	global_load_lds_dwordx4 v128, s[26:27]
	s_mov_b32 m0, s58
	s_nop 0
	global_load_lds_dwordx4 v132, s[56:57]
	s_add_i32 m0, s58, 0x2000
	s_nop 0
	global_load_lds_dwordx4 v128, s[56:57]
	s_mov_b32 m0, s23
	s_nop 0
	global_load_lds_dwordx4 v134, s[28:29]
	s_mov_b32 m0, s41
	s_nop 0
	global_load_lds_dwordx4 v130, s[28:29]
	s_waitcnt vmcnt(8)
	s_waitcnt lgkmcnt(0)
	s_barrier
	v_mfma_f32_16x16x32_bf16 v[60:63], v[150:153], v[182:185], v[60:63]
	v_mfma_f32_16x16x32_bf16 v[56:59], v[158:161], v[182:185], v[56:59]
	v_mfma_f32_16x16x32_bf16 v[44:47], v[150:153], v[190:193], v[44:47]
	v_mfma_f32_16x16x32_bf16 v[40:43], v[158:161], v[190:193], v[40:43]
	v_mfma_f32_16x16x32_bf16 v[28:31], v[150:153], v[198:201], v[28:31]
	v_mfma_f32_16x16x32_bf16 v[24:27], v[158:161], v[198:201], v[24:27]
	v_mfma_f32_16x16x32_bf16 v[12:15], v[150:153], v[206:209], v[12:15]
	v_mfma_f32_16x16x32_bf16 v[8:11], v[158:161], v[206:209], v[8:11]
	v_mfma_f32_16x16x32_bf16 v[60:63], v[154:157], v[186:189], v[60:63]
	v_mfma_f32_16x16x32_bf16 v[56:59], v[162:165], v[186:189], v[56:59]
	v_mfma_f32_16x16x32_bf16 v[44:47], v[154:157], v[194:197], v[44:47]
	v_mfma_f32_16x16x32_bf16 v[40:43], v[162:165], v[194:197], v[40:43]
	v_mfma_f32_16x16x32_bf16 v[28:31], v[154:157], v[202:205], v[28:31]
	v_mfma_f32_16x16x32_bf16 v[24:27], v[162:165], v[202:205], v[24:27]
	v_mfma_f32_16x16x32_bf16 v[12:15], v[154:157], v[210:213], v[12:15]
	v_mfma_f32_16x16x32_bf16 v[8:11], v[162:165], v[210:213], v[8:11]
	v_mfma_f32_16x16x32_bf16 v[52:55], v[166:169], v[182:185], v[52:55]
	v_mfma_f32_16x16x32_bf16 v[48:51], v[174:177], v[182:185], v[48:51]
	v_mfma_f32_16x16x32_bf16 v[36:39], v[166:169], v[190:193], v[36:39]
	v_mfma_f32_16x16x32_bf16 v[32:35], v[174:177], v[190:193], v[32:35]
	v_mfma_f32_16x16x32_bf16 v[20:23], v[166:169], v[198:201], v[20:23]
	v_mfma_f32_16x16x32_bf16 v[16:19], v[174:177], v[198:201], v[16:19]
	v_mfma_f32_16x16x32_bf16 v[4:7], v[166:169], v[206:209], v[4:7]
	v_mfma_f32_16x16x32_bf16 v[0:3], v[174:177], v[206:209], v[0:3]
	v_mfma_f32_16x16x32_bf16 v[52:55], v[170:173], v[186:189], v[52:55]
	v_mfma_f32_16x16x32_bf16 v[48:51], v[178:181], v[186:189], v[48:51]
	v_mfma_f32_16x16x32_bf16 v[36:39], v[170:173], v[194:197], v[36:39]
	v_mfma_f32_16x16x32_bf16 v[32:35], v[178:181], v[194:197], v[32:35]
	v_mfma_f32_16x16x32_bf16 v[20:23], v[170:173], v[202:205], v[20:23]
	v_mfma_f32_16x16x32_bf16 v[16:19], v[178:181], v[202:205], v[16:19]
	v_mfma_f32_16x16x32_bf16 v[4:7], v[170:173], v[210:213], v[4:7]
	v_mfma_f32_16x16x32_bf16 v[0:3], v[178:181], v[210:213], v[0:3]
	s_barrier
	s_add_i32 s56, 0, 0x18000
	s_add_i32 s57, 0, 0x1c000
	v_add_u32_e32 v162, s56, v145
	v_add_u32_e32 v178, s57, v145
	ds_read_b128 v[150:153], v162
	ds_read_b128 v[154:157], v162 offset:1024
	ds_read_b128 v[158:161], v162 offset:2048
	ds_read_b128 v[162:165], v162 offset:3072
	ds_read_b128 v[166:169], v178
	ds_read_b128 v[170:173], v178 offset:1024
	ds_read_b128 v[174:177], v178 offset:2048
	ds_read_b128 v[178:181], v178 offset:3072
	s_add_u32 s28, s28, 0x100000
	s_addc_u32 s29, s29, 0
	s_mov_b32 m0, s42
	ds_read_b128 v[182:185], v149 offset:32768
	ds_read_b128 v[186:189], v149 offset:33792
	ds_read_b128 v[190:193], v149 offset:34816
	ds_read_b128 v[194:197], v149 offset:35840
	ds_read_b128 v[198:201], v149 offset:36864
	ds_read_b128 v[202:205], v149 offset:37888
	ds_read_b128 v[206:209], v149 offset:38912
	ds_read_b128 v[210:213], v149 offset:39936
	global_load_lds_dwordx4 v134, s[28:29]
	s_mov_b32 m0, s43
	s_nop 0
	global_load_lds_dwordx4 v130, s[28:29]
	s_waitcnt vmcnt(8)
	s_waitcnt lgkmcnt(0)
	s_barrier
	v_mfma_f32_16x16x32_bf16 v[124:127], v[150:153], v[182:185], v[124:127]
	v_mfma_f32_16x16x32_bf16 v[120:123], v[158:161], v[182:185], v[120:123]
	v_mfma_f32_16x16x32_bf16 v[108:111], v[150:153], v[190:193], v[108:111]
	v_mfma_f32_16x16x32_bf16 v[104:107], v[158:161], v[190:193], v[104:107]
	v_mfma_f32_16x16x32_bf16 v[92:95], v[150:153], v[198:201], v[92:95]
	v_mfma_f32_16x16x32_bf16 v[88:91], v[158:161], v[198:201], v[88:91]
	v_mfma_f32_16x16x32_bf16 v[76:79], v[150:153], v[206:209], v[76:79]
	v_mfma_f32_16x16x32_bf16 v[72:75], v[158:161], v[206:209], v[72:75]
	v_mfma_f32_16x16x32_bf16 v[124:127], v[154:157], v[186:189], v[124:127]
	v_mfma_f32_16x16x32_bf16 v[120:123], v[162:165], v[186:189], v[120:123]
	v_mfma_f32_16x16x32_bf16 v[108:111], v[154:157], v[194:197], v[108:111]
	v_mfma_f32_16x16x32_bf16 v[104:107], v[162:165], v[194:197], v[104:107]
	v_mfma_f32_16x16x32_bf16 v[92:95], v[154:157], v[202:205], v[92:95]
	v_mfma_f32_16x16x32_bf16 v[88:91], v[162:165], v[202:205], v[88:91]
	v_mfma_f32_16x16x32_bf16 v[76:79], v[154:157], v[210:213], v[76:79]
	v_mfma_f32_16x16x32_bf16 v[72:75], v[162:165], v[210:213], v[72:75]
	v_mfma_f32_16x16x32_bf16 v[116:119], v[166:169], v[182:185], v[116:119]
	v_mfma_f32_16x16x32_bf16 v[112:115], v[174:177], v[182:185], v[112:115]
	v_mfma_f32_16x16x32_bf16 v[100:103], v[166:169], v[190:193], v[100:103]
	v_mfma_f32_16x16x32_bf16 v[96:99], v[174:177], v[190:193], v[96:99]
	v_mfma_f32_16x16x32_bf16 v[84:87], v[166:169], v[198:201], v[84:87]
	v_mfma_f32_16x16x32_bf16 v[80:83], v[174:177], v[198:201], v[80:83]
	v_mfma_f32_16x16x32_bf16 v[68:71], v[166:169], v[206:209], v[68:71]
	v_mfma_f32_16x16x32_bf16 v[64:67], v[174:177], v[206:209], v[64:67]
	v_mfma_f32_16x16x32_bf16 v[116:119], v[170:173], v[186:189], v[116:119]
	v_mfma_f32_16x16x32_bf16 v[112:115], v[178:181], v[186:189], v[112:115]
	v_mfma_f32_16x16x32_bf16 v[100:103], v[170:173], v[194:197], v[100:103]
	v_mfma_f32_16x16x32_bf16 v[96:99], v[178:181], v[194:197], v[96:99]
	v_mfma_f32_16x16x32_bf16 v[84:87], v[170:173], v[202:205], v[84:87]
	v_mfma_f32_16x16x32_bf16 v[80:83], v[178:181], v[202:205], v[80:83]
	v_mfma_f32_16x16x32_bf16 v[68:71], v[170:173], v[210:213], v[68:71]
	v_mfma_f32_16x16x32_bf16 v[64:67], v[178:181], v[210:213], v[64:67]
	s_barrier
	s_add_i32 s28, s56, s39
	s_mov_b32 m0, s28
	ds_read_b128 v[182:185], v149 offset:49152
	ds_read_b128 v[186:189], v149 offset:50176
	ds_read_b128 v[190:193], v149 offset:51200
	ds_read_b128 v[194:197], v149 offset:52224
	ds_read_b128 v[198:201], v149 offset:53248
	ds_read_b128 v[202:205], v149 offset:54272
	ds_read_b128 v[206:209], v149 offset:55296
	ds_read_b128 v[210:213], v149 offset:56320
	global_load_lds_dwordx4 v132, s[98:99]
	s_add_i32 m0, s28, 0x2000
	s_add_u32 s26, s26, 0x100080
	s_addc_u32 s27, s27, 0
	s_add_i32 s28, s57, s39
	global_load_lds_dwordx4 v128, s[98:99]
	s_mov_b32 m0, s28
	s_nop 0
	global_load_lds_dwordx4 v132, s[26:27]
	s_add_i32 m0, s28, 0x2000
	s_nop 0
	global_load_lds_dwordx4 v128, s[26:27]
	s_mov_b32 m0, s44
	s_nop 0
	global_load_lds_dwordx4 v134, s[100:101]
	s_mov_b32 m0, s45
	s_nop 0
	global_load_lds_dwordx4 v130, s[100:101]
	s_waitcnt vmcnt(8)
	s_waitcnt lgkmcnt(0)
	s_barrier
	v_mfma_f32_16x16x32_bf16 v[60:63], v[150:153], v[182:185], v[60:63]
	v_mfma_f32_16x16x32_bf16 v[56:59], v[158:161], v[182:185], v[56:59]
	v_mfma_f32_16x16x32_bf16 v[44:47], v[150:153], v[190:193], v[44:47]
	v_mfma_f32_16x16x32_bf16 v[40:43], v[158:161], v[190:193], v[40:43]
	v_mfma_f32_16x16x32_bf16 v[28:31], v[150:153], v[198:201], v[28:31]
	v_mfma_f32_16x16x32_bf16 v[24:27], v[158:161], v[198:201], v[24:27]
	v_mfma_f32_16x16x32_bf16 v[12:15], v[150:153], v[206:209], v[12:15]
	v_mfma_f32_16x16x32_bf16 v[8:11], v[158:161], v[206:209], v[8:11]
	v_mfma_f32_16x16x32_bf16 v[60:63], v[154:157], v[186:189], v[60:63]
	v_mfma_f32_16x16x32_bf16 v[56:59], v[162:165], v[186:189], v[56:59]
	v_mfma_f32_16x16x32_bf16 v[44:47], v[154:157], v[194:197], v[44:47]
	v_mfma_f32_16x16x32_bf16 v[40:43], v[162:165], v[194:197], v[40:43]
	v_mfma_f32_16x16x32_bf16 v[28:31], v[154:157], v[202:205], v[28:31]
	v_mfma_f32_16x16x32_bf16 v[24:27], v[162:165], v[202:205], v[24:27]
	v_mfma_f32_16x16x32_bf16 v[12:15], v[154:157], v[210:213], v[12:15]
	v_mfma_f32_16x16x32_bf16 v[8:11], v[162:165], v[210:213], v[8:11]
	v_mfma_f32_16x16x32_bf16 v[52:55], v[166:169], v[182:185], v[52:55]
	v_mfma_f32_16x16x32_bf16 v[48:51], v[174:177], v[182:185], v[48:51]
	v_mfma_f32_16x16x32_bf16 v[36:39], v[166:169], v[190:193], v[36:39]
	v_mfma_f32_16x16x32_bf16 v[32:35], v[174:177], v[190:193], v[32:35]
	v_mfma_f32_16x16x32_bf16 v[20:23], v[166:169], v[198:201], v[20:23]
	v_mfma_f32_16x16x32_bf16 v[16:19], v[174:177], v[198:201], v[16:19]
	v_mfma_f32_16x16x32_bf16 v[4:7], v[166:169], v[206:209], v[4:7]
	v_mfma_f32_16x16x32_bf16 v[0:3], v[174:177], v[206:209], v[0:3]
	v_mfma_f32_16x16x32_bf16 v[52:55], v[170:173], v[186:189], v[52:55]
	v_mfma_f32_16x16x32_bf16 v[48:51], v[178:181], v[186:189], v[48:51]
	v_mfma_f32_16x16x32_bf16 v[36:39], v[170:173], v[194:197], v[36:39]
	v_mfma_f32_16x16x32_bf16 v[32:35], v[178:181], v[194:197], v[32:35]
	v_mfma_f32_16x16x32_bf16 v[20:23], v[170:173], v[202:205], v[20:23]
	v_mfma_f32_16x16x32_bf16 v[16:19], v[178:181], v[202:205], v[16:19]
	v_mfma_f32_16x16x32_bf16 v[4:7], v[170:173], v[210:213], v[4:7]
	v_mfma_f32_16x16x32_bf16 v[0:3], v[178:181], v[210:213], v[0:3]
	s_barrier
	s_add_i32 s55, s55, 2
	s_add_u32 s53, s53, 0x100
	s_addc_u32 s54, s54, 0
	s_add_u32 s24, s24, 0x100
	s_addc_u32 s25, s25, 0
	s_cmp_gt_u32 s55, 61
	s_cbranch_scc0 .LBB0_1758
	s_and_b64 vcc, exec, s[12:13]
	s_cbranch_vccz .LBB0_1761
	s_barrier

.LBB0_1963:
	ds_read_b128 v[144:147], v151
	ds_read_b128 v[156:159], v151 offset:1024
	ds_read_b128 v[160:163], v151 offset:2048
	ds_read_b128 v[164:167], v151 offset:3072
	ds_read_b128 v[168:171], v152
	ds_read_b128 v[172:175], v152 offset:1024
	ds_read_b128 v[176:179], v152 offset:2048
	ds_read_b128 v[180:183], v152 offset:3072
	s_add_u32 s28, s26, 0x100
	s_addc_u32 s29, s27, 0
	s_cmpk_eq_i32 s59, 0xa8
	s_cselect_b32 s35, s7, s29
	s_cselect_b32 s34, s6, s28
	s_cselect_b32 s31, s25, s58
	s_cselect_b32 s30, s24, s57
	s_add_i32 m0, s43, 0xc000
	ds_read_b128 v[184:187], v153
	ds_read_b128 v[188:191], v153 offset:1024
	ds_read_b128 v[192:195], v153 offset:2048
	ds_read_b128 v[196:199], v153 offset:3072
	ds_read_b128 v[200:203], v153 offset:4096
	ds_read_b128 v[204:207], v153 offset:5120
	ds_read_b128 v[208:211], v153 offset:6144
	ds_read_b128 v[212:215], v153 offset:7168
	global_load_lds_dwordx4 v138, s[26:27]
	s_add_i32 m0, s43, 0xe000
	s_nop 0
	global_load_lds_dwordx4 v136, s[26:27]
	s_waitcnt vmcnt(8)
	s_waitcnt lgkmcnt(0)
	s_barrier
	v_mfma_f32_16x16x32_bf16 v[124:127], v[144:147], v[184:187], v[124:127]
	v_mfma_f32_16x16x32_bf16 v[120:123], v[160:163], v[184:187], v[120:123]
	v_mfma_f32_16x16x32_bf16 v[108:111], v[144:147], v[192:195], v[108:111]
	v_mfma_f32_16x16x32_bf16 v[104:107], v[160:163], v[192:195], v[104:107]
	v_mfma_f32_16x16x32_bf16 v[92:95], v[144:147], v[200:203], v[92:95]
	v_mfma_f32_16x16x32_bf16 v[88:91], v[160:163], v[200:203], v[88:91]
	v_mfma_f32_16x16x32_bf16 v[76:79], v[144:147], v[208:211], v[76:79]
	v_mfma_f32_16x16x32_bf16 v[72:75], v[160:163], v[208:211], v[72:75]
	v_mfma_f32_16x16x32_bf16 v[124:127], v[156:159], v[188:191], v[124:127]
	v_mfma_f32_16x16x32_bf16 v[120:123], v[164:167], v[188:191], v[120:123]
	v_mfma_f32_16x16x32_bf16 v[108:111], v[156:159], v[196:199], v[108:111]
	v_mfma_f32_16x16x32_bf16 v[104:107], v[164:167], v[196:199], v[104:107]
	v_mfma_f32_16x16x32_bf16 v[92:95], v[156:159], v[204:207], v[92:95]
	v_mfma_f32_16x16x32_bf16 v[88:91], v[164:167], v[204:207], v[88:91]
	v_mfma_f32_16x16x32_bf16 v[76:79], v[156:159], v[212:215], v[76:79]
	v_mfma_f32_16x16x32_bf16 v[72:75], v[164:167], v[212:215], v[72:75]
	v_mfma_f32_16x16x32_bf16 v[116:119], v[168:171], v[184:187], v[116:119]
	v_mfma_f32_16x16x32_bf16 v[112:115], v[176:179], v[184:187], v[112:115]
	v_mfma_f32_16x16x32_bf16 v[100:103], v[168:171], v[192:195], v[100:103]
	v_mfma_f32_16x16x32_bf16 v[96:99], v[176:179], v[192:195], v[96:99]
	v_mfma_f32_16x16x32_bf16 v[84:87], v[168:171], v[200:203], v[84:87]
	v_mfma_f32_16x16x32_bf16 v[80:83], v[176:179], v[200:203], v[80:83]
	v_mfma_f32_16x16x32_bf16 v[68:71], v[168:171], v[208:211], v[68:71]
	v_mfma_f32_16x16x32_bf16 v[64:67], v[176:179], v[208:211], v[64:67]
	v_mfma_f32_16x16x32_bf16 v[116:119], v[172:175], v[188:191], v[116:119]
	v_mfma_f32_16x16x32_bf16 v[112:115], v[180:183], v[188:191], v[112:115]
	v_mfma_f32_16x16x32_bf16 v[100:103], v[172:175], v[196:199], v[100:103]
	v_mfma_f32_16x16x32_bf16 v[96:99], v[180:183], v[196:199], v[96:99]
	v_mfma_f32_16x16x32_bf16 v[84:87], v[172:175], v[204:207], v[84:87]
	v_mfma_f32_16x16x32_bf16 v[80:83], v[180:183], v[204:207], v[80:83]
	v_mfma_f32_16x16x32_bf16 v[68:71], v[172:175], v[212:215], v[68:71]
	v_mfma_f32_16x16x32_bf16 v[64:67], v[180:183], v[212:215], v[64:67]
	s_barrier
	s_add_u32 s98, s30, 0x80
	s_addc_u32 s99, s31, 0
	s_add_u32 s100, s34, 0x80
	s_addc_u32 s101, s35, 0
	s_add_i32 s26, s52, s42
	s_mov_b32 m0, s26
	ds_read_b128 v[184:187], v153 offset:16384
	ds_read_b128 v[188:191], v153 offset:17408
	ds_read_b128 v[192:195], v153 offset:18432
	ds_read_b128 v[196:199], v153 offset:19456
	ds_read_b128 v[200:203], v153 offset:20480
	ds_read_b128 v[204:207], v153 offset:21504
	ds_read_b128 v[208:211], v153 offset:22528
	ds_read_b128 v[212:215], v153 offset:23552
	global_load_lds_dwordx4 v130, s[30:31]
	s_add_i32 m0, s26, 0x2000
	s_add_u32 s26, s30, 0x2b0000
	s_addc_u32 s27, s31, 0
	s_add_i32 s60, s53, s42
	global_load_lds_dwordx4 v134, s[30:31]
	s_mov_b32 m0, s60
	s_nop 0
	global_load_lds_dwordx4 v130, s[26:27]
	s_add_i32 m0, s60, 0x2000
	s_nop 0
	global_load_lds_dwordx4 v134, s[26:27]
	s_mov_b32 m0, s43
	s_nop 0
	global_load_lds_dwordx4 v128, s[34:35]
	s_mov_b32 m0, s44
	s_nop 0
	global_load_lds_dwordx4 v132, s[34:35]
	s_waitcnt vmcnt(8)
	s_waitcnt lgkmcnt(0)
	s_barrier
	v_mfma_f32_16x16x32_bf16 v[60:63], v[144:147], v[184:187], v[60:63]
	v_mfma_f32_16x16x32_bf16 v[56:59], v[160:163], v[184:187], v[56:59]
	v_mfma_f32_16x16x32_bf16 v[44:47], v[144:147], v[192:195], v[44:47]
	v_mfma_f32_16x16x32_bf16 v[40:43], v[160:163], v[192:195], v[40:43]
	v_mfma_f32_16x16x32_bf16 v[28:31], v[144:147], v[200:203], v[28:31]
	v_mfma_f32_16x16x32_bf16 v[24:27], v[160:163], v[200:203], v[24:27]
	v_mfma_f32_16x16x32_bf16 v[12:15], v[144:147], v[208:211], v[12:15]
	v_mfma_f32_16x16x32_bf16 v[8:11], v[160:163], v[208:211], v[8:11]
	v_mfma_f32_16x16x32_bf16 v[60:63], v[156:159], v[188:191], v[60:63]
	v_mfma_f32_16x16x32_bf16 v[56:59], v[164:167], v[188:191], v[56:59]
	v_mfma_f32_16x16x32_bf16 v[44:47], v[156:159], v[196:199], v[44:47]
	v_mfma_f32_16x16x32_bf16 v[40:43], v[164:167], v[196:199], v[40:43]
	v_mfma_f32_16x16x32_bf16 v[28:31], v[156:159], v[204:207], v[28:31]
	v_mfma_f32_16x16x32_bf16 v[24:27], v[164:167], v[204:207], v[24:27]
	v_mfma_f32_16x16x32_bf16 v[12:15], v[156:159], v[212:215], v[12:15]
	v_mfma_f32_16x16x32_bf16 v[8:11], v[164:167], v[212:215], v[8:11]
	v_mfma_f32_16x16x32_bf16 v[52:55], v[168:171], v[184:187], v[52:55]
	v_mfma_f32_16x16x32_bf16 v[48:51], v[176:179], v[184:187], v[48:51]
	v_mfma_f32_16x16x32_bf16 v[36:39], v[168:171], v[192:195], v[36:39]
	v_mfma_f32_16x16x32_bf16 v[32:35], v[176:179], v[192:195], v[32:35]
	v_mfma_f32_16x16x32_bf16 v[20:23], v[168:171], v[200:203], v[20:23]
	v_mfma_f32_16x16x32_bf16 v[16:19], v[176:179], v[200:203], v[16:19]
	v_mfma_f32_16x16x32_bf16 v[4:7], v[168:171], v[208:211], v[4:7]
	v_mfma_f32_16x16x32_bf16 v[0:3], v[176:179], v[208:211], v[0:3]
	v_mfma_f32_16x16x32_bf16 v[52:55], v[172:175], v[188:191], v[52:55]
	v_mfma_f32_16x16x32_bf16 v[48:51], v[180:183], v[188:191], v[48:51]
	v_mfma_f32_16x16x32_bf16 v[36:39], v[172:175], v[196:199], v[36:39]
	v_mfma_f32_16x16x32_bf16 v[32:35], v[180:183], v[196:199], v[32:35]
	v_mfma_f32_16x16x32_bf16 v[20:23], v[172:175], v[204:207], v[20:23]
	v_mfma_f32_16x16x32_bf16 v[16:19], v[180:183], v[204:207], v[16:19]
	v_mfma_f32_16x16x32_bf16 v[4:7], v[172:175], v[212:215], v[4:7]
	v_mfma_f32_16x16x32_bf16 v[0:3], v[180:183], v[212:215], v[0:3]
	s_barrier
	s_add_i32 s60, 0, 0x18000
	v_add_u32_e32 v155, s60, v149
	s_add_i32 s61, 0, 0x1c000
	ds_read_b128 v[144:147], v155
	ds_read_b128 v[156:159], v155 offset:1024
	ds_read_b128 v[160:163], v155 offset:2048
	ds_read_b128 v[164:167], v155 offset:3072
	v_add_u32_e32 v155, s61, v149
	ds_read_b128 v[168:171], v155
	ds_read_b128 v[172:175], v155 offset:1024
	ds_read_b128 v[176:179], v155 offset:2048
	ds_read_b128 v[180:183], v155 offset:3072
	s_add_u32 s26, s34, 0x2b0000
	s_addc_u32 s27, s35, 0
	s_mov_b32 m0, s45
	ds_read_b128 v[184:187], v153 offset:32768
	ds_read_b128 v[188:191], v153 offset:33792
	ds_read_b128 v[192:195], v153 offset:34816
	ds_read_b128 v[196:199], v153 offset:35840
	ds_read_b128 v[200:203], v153 offset:36864
	ds_read_b128 v[204:207], v153 offset:37888
	ds_read_b128 v[208:211], v153 offset:38912
	ds_read_b128 v[212:215], v153 offset:39936
	global_load_lds_dwordx4 v128, s[26:27]
	s_mov_b32 m0, s46
	s_nop 0
	global_load_lds_dwordx4 v132, s[26:27]
	s_waitcnt vmcnt(8)
	s_waitcnt lgkmcnt(0)
	s_barrier
	v_mfma_f32_16x16x32_bf16 v[124:127], v[144:147], v[184:187], v[124:127]
	v_mfma_f32_16x16x32_bf16 v[120:123], v[160:163], v[184:187], v[120:123]
	v_mfma_f32_16x16x32_bf16 v[108:111], v[144:147], v[192:195], v[108:111]
	v_mfma_f32_16x16x32_bf16 v[104:107], v[160:163], v[192:195], v[104:107]
	v_mfma_f32_16x16x32_bf16 v[92:95], v[144:147], v[200:203], v[92:95]
	v_mfma_f32_16x16x32_bf16 v[88:91], v[160:163], v[200:203], v[88:91]
	v_mfma_f32_16x16x32_bf16 v[76:79], v[144:147], v[208:211], v[76:79]
	v_mfma_f32_16x16x32_bf16 v[72:75], v[160:163], v[208:211], v[72:75]
	v_mfma_f32_16x16x32_bf16 v[124:127], v[156:159], v[188:191], v[124:127]
	v_mfma_f32_16x16x32_bf16 v[120:123], v[164:167], v[188:191], v[120:123]
	v_mfma_f32_16x16x32_bf16 v[108:111], v[156:159], v[196:199], v[108:111]
	v_mfma_f32_16x16x32_bf16 v[104:107], v[164:167], v[196:199], v[104:107]
	v_mfma_f32_16x16x32_bf16 v[92:95], v[156:159], v[204:207], v[92:95]
	v_mfma_f32_16x16x32_bf16 v[88:91], v[164:167], v[204:207], v[88:91]
	v_mfma_f32_16x16x32_bf16 v[76:79], v[156:159], v[212:215], v[76:79]
	v_mfma_f32_16x16x32_bf16 v[72:75], v[164:167], v[212:215], v[72:75]
	v_mfma_f32_16x16x32_bf16 v[116:119], v[168:171], v[184:187], v[116:119]
	v_mfma_f32_16x16x32_bf16 v[112:115], v[176:179], v[184:187], v[112:115]
	v_mfma_f32_16x16x32_bf16 v[100:103], v[168:171], v[192:195], v[100:103]
	v_mfma_f32_16x16x32_bf16 v[96:99], v[176:179], v[192:195], v[96:99]
	v_mfma_f32_16x16x32_bf16 v[84:87], v[168:171], v[200:203], v[84:87]
	v_mfma_f32_16x16x32_bf16 v[80:83], v[176:179], v[200:203], v[80:83]
	v_mfma_f32_16x16x32_bf16 v[68:71], v[168:171], v[208:211], v[68:71]
	v_mfma_f32_16x16x32_bf16 v[64:67], v[176:179], v[208:211], v[64:67]
	v_mfma_f32_16x16x32_bf16 v[116:119], v[172:175], v[188:191], v[116:119]
	v_mfma_f32_16x16x32_bf16 v[112:115], v[180:183], v[188:191], v[112:115]
	v_mfma_f32_16x16x32_bf16 v[100:103], v[172:175], v[196:199], v[100:103]
	v_mfma_f32_16x16x32_bf16 v[96:99], v[180:183], v[196:199], v[96:99]
	v_mfma_f32_16x16x32_bf16 v[84:87], v[172:175], v[204:207], v[84:87]
	v_mfma_f32_16x16x32_bf16 v[80:83], v[180:183], v[204:207], v[80:83]
	v_mfma_f32_16x16x32_bf16 v[68:71], v[172:175], v[212:215], v[68:71]
	v_mfma_f32_16x16x32_bf16 v[64:67], v[180:183], v[212:215], v[64:67]
	s_barrier
	s_add_i32 s26, s60, s42
	s_mov_b32 m0, s26
	ds_read_b128 v[184:187], v153 offset:49152
	ds_read_b128 v[188:191], v153 offset:50176
	ds_read_b128 v[192:195], v153 offset:51200
	ds_read_b128 v[196:199], v153 offset:52224
	ds_read_b128 v[200:203], v153 offset:53248
	ds_read_b128 v[204:207], v153 offset:54272
	ds_read_b128 v[208:211], v153 offset:55296
	ds_read_b128 v[212:215], v153 offset:56320
	global_load_lds_dwordx4 v130, s[98:99]
	s_add_i32 m0, s26, 0x2000
	s_add_u32 s26, s30, 0x2b0080
	s_addc_u32 s27, s31, 0
	s_add_i32 s30, s61, s42
	global_load_lds_dwordx4 v134, s[98:99]
	s_mov_b32 m0, s30
	s_nop 0
	global_load_lds_dwordx4 v130, s[26:27]
	s_add_i32 m0, s30, 0x2000
	s_nop 0
	global_load_lds_dwordx4 v134, s[26:27]
	s_mov_b32 m0, s50
	s_nop 0
	global_load_lds_dwordx4 v128, s[100:101]
	s_mov_b32 m0, s51
	s_nop 0
	global_load_lds_dwordx4 v132, s[100:101]
	s_waitcnt vmcnt(8)
	s_waitcnt lgkmcnt(0)
	s_barrier
	v_mfma_f32_16x16x32_bf16 v[60:63], v[144:147], v[184:187], v[60:63]
	v_mfma_f32_16x16x32_bf16 v[56:59], v[160:163], v[184:187], v[56:59]
	v_mfma_f32_16x16x32_bf16 v[44:47], v[144:147], v[192:195], v[44:47]
	v_mfma_f32_16x16x32_bf16 v[40:43], v[160:163], v[192:195], v[40:43]
	v_mfma_f32_16x16x32_bf16 v[28:31], v[144:147], v[200:203], v[28:31]
	v_mfma_f32_16x16x32_bf16 v[24:27], v[160:163], v[200:203], v[24:27]
	v_mfma_f32_16x16x32_bf16 v[12:15], v[144:147], v[208:211], v[12:15]
	v_mfma_f32_16x16x32_bf16 v[8:11], v[160:163], v[208:211], v[8:11]
	v_mfma_f32_16x16x32_bf16 v[60:63], v[156:159], v[188:191], v[60:63]
	v_mfma_f32_16x16x32_bf16 v[56:59], v[164:167], v[188:191], v[56:59]
	v_mfma_f32_16x16x32_bf16 v[44:47], v[156:159], v[196:199], v[44:47]
	v_mfma_f32_16x16x32_bf16 v[40:43], v[164:167], v[196:199], v[40:43]
	v_mfma_f32_16x16x32_bf16 v[28:31], v[156:159], v[204:207], v[28:31]
	v_mfma_f32_16x16x32_bf16 v[24:27], v[164:167], v[204:207], v[24:27]
	v_mfma_f32_16x16x32_bf16 v[12:15], v[156:159], v[212:215], v[12:15]
	v_mfma_f32_16x16x32_bf16 v[8:11], v[164:167], v[212:215], v[8:11]
	v_mfma_f32_16x16x32_bf16 v[52:55], v[168:171], v[184:187], v[52:55]
	v_mfma_f32_16x16x32_bf16 v[48:51], v[176:179], v[184:187], v[48:51]
	v_mfma_f32_16x16x32_bf16 v[36:39], v[168:171], v[192:195], v[36:39]
	v_mfma_f32_16x16x32_bf16 v[32:35], v[176:179], v[192:195], v[32:35]
	v_mfma_f32_16x16x32_bf16 v[20:23], v[168:171], v[200:203], v[20:23]
	v_mfma_f32_16x16x32_bf16 v[16:19], v[176:179], v[200:203], v[16:19]
	v_mfma_f32_16x16x32_bf16 v[4:7], v[168:171], v[208:211], v[4:7]
	v_mfma_f32_16x16x32_bf16 v[0:3], v[176:179], v[208:211], v[0:3]
	v_mfma_f32_16x16x32_bf16 v[52:55], v[172:175], v[188:191], v[52:55]
	v_mfma_f32_16x16x32_bf16 v[48:51], v[180:183], v[188:191], v[48:51]
	v_mfma_f32_16x16x32_bf16 v[36:39], v[172:175], v[196:199], v[36:39]
	v_mfma_f32_16x16x32_bf16 v[32:35], v[180:183], v[196:199], v[32:35]
	v_mfma_f32_16x16x32_bf16 v[20:23], v[172:175], v[204:207], v[20:23]
	v_mfma_f32_16x16x32_bf16 v[16:19], v[180:183], v[204:207], v[16:19]
	v_mfma_f32_16x16x32_bf16 v[4:7], v[172:175], v[212:215], v[4:7]
	v_mfma_f32_16x16x32_bf16 v[0:3], v[180:183], v[212:215], v[0:3]
	s_barrier
	s_add_i32 s59, s59, 2
	s_add_u32 s57, s57, 0x100
	s_addc_u32 s58, s58, 0
	s_cmpk_gt_u32 s59, 0xa9
	s_mov_b64 s[26:27], s[28:29]
	s_cbranch_scc0 .LBB0_1963
	s_and_b64 vcc, exec, s[22:23]
	s_cbranch_vccz .LBB0_1966
	s_barrier
